# P0 weight transpose/convert loop rewritten by hand: generic item decode, next item's 16 loads prefetched while the current item goes through LDS
# speedup vs baseline: 1.0047x; 1.0032x over previous
.LBB0_307:
	s_cmpk_gt_i32 s52, 0x1b7f
	s_cbranch_scc1 .LBB0_334
	v_readlane_b32 s82, v250, 2
	v_readlane_b32 s83, v250, 3
	v_and_b32_e32 v72, 63, v222
	v_lshrrev_b32_e32 v68, 4, v72
	v_and_b32_e32 v69, 15, v72
	v_lshlrev_b32_e32 v69, 4, v69
	v_lshrrev_b32_e32 v70, 3, v72
	v_and_b32_e32 v71, 7, v72
	v_lshlrev_b32_e32 v73, 4, v71
	s_mul_i32 s3, s55, 0x4100
	v_mul_u32_u24_e32 v66, 0x104, v68
	v_add3_u32 v66, v66, v69, s3
	v_mul_u32_u24_e32 v67, 0x820, v71
	v_lshl_add_u32 v67, v70, 2, v67
	v_add_u32_e32 v67, s3, v67
	v_mov_b32_e32 v71, v73
	s_mov_b32 s11, s52
	s_mov_b32 s51, 1
	s_cmp_lt_u32 s11, 0x1b80
	s_cbranch_scc0 .Ltr_done_1
	s_cmp_lt_u32 s11, 0x1080
	s_cbranch_scc0 .Ltr_B_2
	s_cmp_ge_u32 s11, 0x840
	s_cselect_b32 s2, 1, 0
	s_mul_i32 s3, s2, 0x840
	s_sub_u32 s3, s11, s3
	s_cmp_lt_u32 s3, 0x580
	s_cbranch_scc0 .Ltr_FO_3
	s_mul_i32 s4, s3, 745
	s_lshr_b32 s4, s4, 16
	s_mul_i32 s5, s4, 88
	s_sub_u32 s5, s3, s5
	s_lshr_b32 s31, s5, 2
	s_lshl_b32 s31, s31, 7
	s_bfe_u32 s32, s5, 0x10001
	s_mul_i32 s32, s32, 2816
	s_add_u32 s31, s31, s32
	s_and_b32 s32, s5, 1
	s_lshl_b32 s32, s32, 6
	s_add_u32 s31, s31, s32
	s_lshl_b32 s32, s4, 6
	s_lshl_b32 s35, s5, 6
	s_cmp_eq_u32 s2, 1
	s_cselect_b32 s36, 0x98, 0x28
	s_mov_b32 s4, 0x12000000
	s_cselect_b32 s4, 0x1f00000, s4
	s_movk_i32 s18, 0x5800
	s_movk_i32 s19, 0x800
	s_branch .Ltr_com_7
.Ltr_FO_3:
	s_sub_u32 s3, s3, 0x580
	s_lshr_b32 s4, s3, 4
	s_and_b32 s5, s3, 15
	s_lshl_b32 s31, s5, 6
	s_lshl_b32 s32, s4, 6
	s_mov_b32 s35, s31
	s_cmp_eq_u32 s2, 1
	s_cselect_b32 s36, 0xa0, 0x30
	s_mov_b32 s4, 0x12b00000
	s_cselect_b32 s4, 0x2a00000, s4
	s_movk_i32 s18, 0x1000
	s_movk_i32 s19, 0x1600
	s_branch .Ltr_com_7
.Ltr_B_2:
	s_sub_u32 s3, s11, 0x1080
	s_movk_i32 s36, 0x40
	s_mov_b32 s18, 0x8060
	s_movk_i32 s19, 0x800
	s_cmp_lt_u32 s3, 0x400
	s_cbranch_scc0 .Ltr_V_4
	s_lshr_b32 s32, s3, 6
	s_lshl_b32 s32, s32, 6
	s_and_b32 s35, s3, 63
	s_lshl_b32 s35, s35, 6
	s_cmp_ge_u32 s35, 0x400
	s_cselect_b32 s31, 0x400, 0
	s_cmp_ge_u32 s35, 0x800
	s_cselect_b32 s31, 0x408, s31
	s_add_u32 s31, s31, s35
	s_mov_b32 s4, 0x800000
	s_branch .Ltr_com_7
.Ltr_V_4:
	s_sub_u32 s3, s3, 0x400
	s_cmp_lt_u32 s3, 0x200
	s_cbranch_scc0 .Ltr_G_5
	s_lshr_b32 s32, s3, 5
	s_lshl_b32 s32, s32, 6
	s_and_b32 s35, s3, 31
	s_lshl_b32 s35, s35, 6
	s_cmp_ge_u32 s35, 0x400
	s_movk_i32 s31, 0x400
	s_cselect_b32 s31, 0x1008, s31
	s_add_u32 s31, s31, s35
	s_mov_b32 s4, 0x1100000
	s_branch .Ltr_com_7
.Ltr_G_5:
	s_sub_u32 s3, s3, 0x200
	s_cmp_lt_u32 s3, 0x200
	s_cbranch_scc0 .Ltr_S_6
	s_lshr_b32 s32, s3, 5
	s_lshl_b32 s32, s32, 6
	s_and_b32 s35, s3, 31
	s_lshl_b32 s35, s35, 6
	s_add_u32 s31, s35, 0x1818
	s_mov_b32 s4, 0x1500000
	s_branch .Ltr_com_7
.Ltr_S_6:
	s_sub_u32 s3, s3, 0x200
	s_lshr_b32 s2, s3, 8
	s_and_b32 s3, s3, 255
	s_lshr_b32 s32, s3, 4
	s_lshl_b32 s32, s32, 6
	s_and_b32 s35, s3, 15
	s_lshl_b32 s35, s35, 6
	s_mov_b32 s31, s35
	s_lshl_b32 s36, s2, 3
	s_add_u32 s36, s36, 0x78
	s_lshl_b32 s4, s2, 21
	s_add_u32 s4, s4, 0x1900000
	s_movk_i32 s18, 0x1000
.Ltr_com_7:
	s_load_dwordx2 s[16:17], s[82:83], s36
	s_mul_i32 s5, s35, s19
	s_lshl_b32 s2, s32, 1
	s_add_u32 s5, s5, s2
	s_add_u32 s20, s74, s4
	s_addc_u32 s21, s75, 0
	s_add_u32 s20, s20, s5
	s_addc_u32 s21, s21, 0
	s_mul_i32 s5, s32, s18
	s_lshl_b32 s2, s31, 2
	s_add_u32 s5, s5, s2
	s_waitcnt lgkmcnt(0)
	s_add_u32 s16, s16, s5
	s_addc_u32 s17, s17, 0
	v_mul_lo_u32 v64, v68, s18
	v_add_u32_e32 v64, v64, v69
	s_lshl_b32 s2, s18, 2
	global_load_dwordx4 v[0:3], v64, s[16:17]
	s_add_u32 s16, s16, s2
	s_addc_u32 s17, s17, 0
	global_load_dwordx4 v[4:7], v64, s[16:17]
	s_add_u32 s16, s16, s2
	s_addc_u32 s17, s17, 0
	global_load_dwordx4 v[8:11], v64, s[16:17]
	s_add_u32 s16, s16, s2
	s_addc_u32 s17, s17, 0
	global_load_dwordx4 v[12:15], v64, s[16:17]
	s_add_u32 s16, s16, s2
	s_addc_u32 s17, s17, 0
	global_load_dwordx4 v[16:19], v64, s[16:17]
	s_add_u32 s16, s16, s2
	s_addc_u32 s17, s17, 0
	global_load_dwordx4 v[20:23], v64, s[16:17]
	s_add_u32 s16, s16, s2
	s_addc_u32 s17, s17, 0
	global_load_dwordx4 v[24:27], v64, s[16:17]
	s_add_u32 s16, s16, s2
	s_addc_u32 s17, s17, 0
	global_load_dwordx4 v[28:31], v64, s[16:17]
	s_add_u32 s16, s16, s2
	s_addc_u32 s17, s17, 0
	global_load_dwordx4 v[32:35], v64, s[16:17]
	s_add_u32 s16, s16, s2
	s_addc_u32 s17, s17, 0
	global_load_dwordx4 v[36:39], v64, s[16:17]
	s_add_u32 s16, s16, s2
	s_addc_u32 s17, s17, 0
	global_load_dwordx4 v[40:43], v64, s[16:17]
	s_add_u32 s16, s16, s2
	s_addc_u32 s17, s17, 0
	global_load_dwordx4 v[44:47], v64, s[16:17]
	s_add_u32 s16, s16, s2
	s_addc_u32 s17, s17, 0
	global_load_dwordx4 v[48:51], v64, s[16:17]
	s_add_u32 s16, s16, s2
	s_addc_u32 s17, s17, 0
	global_load_dwordx4 v[52:55], v64, s[16:17]
	s_add_u32 s16, s16, s2
	s_addc_u32 s17, s17, 0
	global_load_dwordx4 v[56:59], v64, s[16:17]
	s_add_u32 s16, s16, s2
	s_addc_u32 s17, s17, 0
	global_load_dwordx4 v[60:63], v64, s[16:17]
.Ltr_loop_8:
	s_mov_b64 s[48:49], s[20:21]
	s_mov_b32 s50, s19
	s_add_u32 s11, s11, s54
	s_cmp_lt_u32 s11, 0x1b80
	s_cbranch_scc0 .Ltr_nonext_9
	s_cmp_lt_u32 s11, 0x1080
	s_cbranch_scc0 .Ltr_B_11
	s_cmp_ge_u32 s11, 0x840
	s_cselect_b32 s2, 1, 0
	s_mul_i32 s3, s2, 0x840
	s_sub_u32 s3, s11, s3
	s_cmp_lt_u32 s3, 0x580
	s_cbranch_scc0 .Ltr_FO_12
	s_mul_i32 s4, s3, 745
	s_lshr_b32 s4, s4, 16
	s_mul_i32 s5, s4, 88
	s_sub_u32 s5, s3, s5
	s_lshr_b32 s31, s5, 2
	s_lshl_b32 s31, s31, 7
	s_bfe_u32 s32, s5, 0x10001
	s_mul_i32 s32, s32, 2816
	s_add_u32 s31, s31, s32
	s_and_b32 s32, s5, 1
	s_lshl_b32 s32, s32, 6
	s_add_u32 s31, s31, s32
	s_lshl_b32 s32, s4, 6
	s_lshl_b32 s35, s5, 6
	s_cmp_eq_u32 s2, 1
	s_cselect_b32 s36, 0x98, 0x28
	s_mov_b32 s4, 0x12000000
	s_cselect_b32 s4, 0x1f00000, s4
	s_movk_i32 s18, 0x5800
	s_movk_i32 s19, 0x800
	s_branch .Ltr_com_16

.Ltr_com_16:
	s_load_dwordx2 s[16:17], s[82:83], s36
	s_mul_i32 s5, s35, s19
	s_lshl_b32 s2, s32, 1
	s_add_u32 s5, s5, s2
	s_add_u32 s20, s74, s4
	s_addc_u32 s21, s75, 0
	s_add_u32 s20, s20, s5
	s_addc_u32 s21, s21, 0
	s_mul_i32 s5, s32, s18
	s_lshl_b32 s2, s31, 2
	s_add_u32 s5, s5, s2
	s_waitcnt lgkmcnt(0)
	s_add_u32 s16, s16, s5
	s_addc_u32 s17, s17, 0
	v_mul_lo_u32 v64, v68, s18
	v_add_u32_e32 v64, v64, v69
	s_lshl_b32 s2, s18, 2
	global_load_dwordx4 v[98:101], v64, s[16:17]
	s_add_u32 s16, s16, s2
	s_addc_u32 s17, s17, 0
	global_load_dwordx4 v[102:105], v64, s[16:17]
	s_add_u32 s16, s16, s2
	s_addc_u32 s17, s17, 0
	global_load_dwordx4 v[106:109], v64, s[16:17]
	s_add_u32 s16, s16, s2
	s_addc_u32 s17, s17, 0
	global_load_dwordx4 v[110:113], v64, s[16:17]
	s_add_u32 s16, s16, s2
	s_addc_u32 s17, s17, 0
	global_load_dwordx4 v[114:117], v64, s[16:17]
	s_add_u32 s16, s16, s2
	s_addc_u32 s17, s17, 0
	global_load_dwordx4 v[118:121], v64, s[16:17]
	s_add_u32 s16, s16, s2
	s_addc_u32 s17, s17, 0
	global_load_dwordx4 v[122:125], v64, s[16:17]
	s_add_u32 s16, s16, s2
	s_addc_u32 s17, s17, 0
	global_load_dwordx4 v[126:129], v64, s[16:17]
	s_add_u32 s16, s16, s2
	s_addc_u32 s17, s17, 0
	global_load_dwordx4 v[130:133], v64, s[16:17]
	s_add_u32 s16, s16, s2
	s_addc_u32 s17, s17, 0
	global_load_dwordx4 v[134:137], v64, s[16:17]
	s_add_u32 s16, s16, s2
	s_addc_u32 s17, s17, 0
	global_load_dwordx4 v[138:141], v64, s[16:17]
	s_add_u32 s16, s16, s2
	s_addc_u32 s17, s17, 0
	global_load_dwordx4 v[142:145], v64, s[16:17]
	s_add_u32 s16, s16, s2
	s_addc_u32 s17, s17, 0
	global_load_dwordx4 v[146:149], v64, s[16:17]
	s_add_u32 s16, s16, s2
	s_addc_u32 s17, s17, 0
	global_load_dwordx4 v[150:153], v64, s[16:17]
	s_add_u32 s16, s16, s2
	s_addc_u32 s17, s17, 0
	global_load_dwordx4 v[154:157], v64, s[16:17]
	s_add_u32 s16, s16, s2
	s_addc_u32 s17, s17, 0
	global_load_dwordx4 v[158:161], v64, s[16:17]
	s_cmp_eq_u32 s51, 1
	s_cbranch_scc1 .Ltr_f1_17
	s_waitcnt vmcnt(24)
	s_branch .Ltr_proc_10
.Ltr_f1_17:
	s_waitcnt vmcnt(16)
	s_branch .Ltr_proc_10
.Ltr_nonext_9:
	s_cmp_eq_u32 s51, 1
	s_cbranch_scc1 .Ltr_f2_18
	s_waitcnt vmcnt(8)
	s_branch .Ltr_proc_10

.Ltr_proc_10:
	s_mov_b32 s51, 0
	ds_write_b32 v66, v0 offset:0
	ds_write_b32 v66, v1 offset:4
	ds_write_b32 v66, v2 offset:8
	ds_write_b32 v66, v3 offset:12
	ds_write_b32 v66, v4 offset:1040
	ds_write_b32 v66, v5 offset:1044
	ds_write_b32 v66, v6 offset:1048
	ds_write_b32 v66, v7 offset:1052
	ds_write_b32 v66, v8 offset:2080
	ds_write_b32 v66, v9 offset:2084
	ds_write_b32 v66, v10 offset:2088
	ds_write_b32 v66, v11 offset:2092
	ds_write_b32 v66, v12 offset:3120
	ds_write_b32 v66, v13 offset:3124
	ds_write_b32 v66, v14 offset:3128
	ds_write_b32 v66, v15 offset:3132
	ds_write_b32 v66, v16 offset:4160
	ds_write_b32 v66, v17 offset:4164
	ds_write_b32 v66, v18 offset:4168
	ds_write_b32 v66, v19 offset:4172
	ds_write_b32 v66, v20 offset:5200
	ds_write_b32 v66, v21 offset:5204
	ds_write_b32 v66, v22 offset:5208
	ds_write_b32 v66, v23 offset:5212
	ds_write_b32 v66, v24 offset:6240
	ds_write_b32 v66, v25 offset:6244
	ds_write_b32 v66, v26 offset:6248
	ds_write_b32 v66, v27 offset:6252
	ds_write_b32 v66, v28 offset:7280
	ds_write_b32 v66, v29 offset:7284
	ds_write_b32 v66, v30 offset:7288
	ds_write_b32 v66, v31 offset:7292
	ds_write_b32 v66, v32 offset:8320
	ds_write_b32 v66, v33 offset:8324
	ds_write_b32 v66, v34 offset:8328
	ds_write_b32 v66, v35 offset:8332
	ds_write_b32 v66, v36 offset:9360
	ds_write_b32 v66, v37 offset:9364
	ds_write_b32 v66, v38 offset:9368
	ds_write_b32 v66, v39 offset:9372
	ds_write_b32 v66, v40 offset:10400
	ds_write_b32 v66, v41 offset:10404
	ds_write_b32 v66, v42 offset:10408
	ds_write_b32 v66, v43 offset:10412
	ds_write_b32 v66, v44 offset:11440
	ds_write_b32 v66, v45 offset:11444
	ds_write_b32 v66, v46 offset:11448
	ds_write_b32 v66, v47 offset:11452
	ds_write_b32 v66, v48 offset:12480
	ds_write_b32 v66, v49 offset:12484
	ds_write_b32 v66, v50 offset:12488
	ds_write_b32 v66, v51 offset:12492
	ds_write_b32 v66, v52 offset:13520
	ds_write_b32 v66, v53 offset:13524
	ds_write_b32 v66, v54 offset:13528
	ds_write_b32 v66, v55 offset:13532
	ds_write_b32 v66, v56 offset:14560
	ds_write_b32 v66, v57 offset:14564
	ds_write_b32 v66, v58 offset:14568
	ds_write_b32 v66, v59 offset:14572
	ds_write_b32 v66, v60 offset:15600
	ds_write_b32 v66, v61 offset:15604
	ds_write_b32 v66, v62 offset:15608
	ds_write_b32 v66, v63 offset:15612
	s_waitcnt lgkmcnt(0)
	v_mul_lo_u32 v65, v70, s50
	v_add_u32_e32 v65, v65, v71
	s_lshl_b32 s2, s50, 3
	ds_read_b32 v162, v67 offset:0
	ds_read_b32 v163, v67 offset:260
	ds_read_b32 v164, v67 offset:520
	ds_read_b32 v165, v67 offset:780
	ds_read_b32 v166, v67 offset:1040
	ds_read_b32 v167, v67 offset:1300
	ds_read_b32 v168, v67 offset:1560
	ds_read_b32 v169, v67 offset:1820
	ds_read_b32 v170, v67 offset:32
	ds_read_b32 v171, v67 offset:292
	ds_read_b32 v172, v67 offset:552
	ds_read_b32 v173, v67 offset:812
	ds_read_b32 v174, v67 offset:1072
	ds_read_b32 v175, v67 offset:1332
	ds_read_b32 v176, v67 offset:1592
	ds_read_b32 v177, v67 offset:1852
	ds_read_b32 v178, v67 offset:64
	ds_read_b32 v179, v67 offset:324
	ds_read_b32 v180, v67 offset:584
	ds_read_b32 v181, v67 offset:844
	ds_read_b32 v182, v67 offset:1104
	ds_read_b32 v183, v67 offset:1364
	ds_read_b32 v184, v67 offset:1624
	ds_read_b32 v185, v67 offset:1884
	ds_read_b32 v186, v67 offset:96
	ds_read_b32 v187, v67 offset:356
	ds_read_b32 v191, v67 offset:616
	ds_read_b32 v192, v67 offset:876
	ds_read_b32 v193, v67 offset:1136
	ds_read_b32 v194, v67 offset:1396
	ds_read_b32 v195, v67 offset:1656
	ds_read_b32 v196, v67 offset:1916
	ds_read_b32 v197, v67 offset:128
	ds_read_b32 v198, v67 offset:388
	ds_read_b32 v199, v67 offset:648
	ds_read_b32 v200, v67 offset:908
	ds_read_b32 v201, v67 offset:1168
	ds_read_b32 v202, v67 offset:1428
	ds_read_b32 v203, v67 offset:1688
	ds_read_b32 v204, v67 offset:1948
	ds_read_b32 v205, v67 offset:160
	ds_read_b32 v206, v67 offset:420
	ds_read_b32 v207, v67 offset:680
	ds_read_b32 v208, v67 offset:940
	ds_read_b32 v209, v67 offset:1200
	ds_read_b32 v210, v67 offset:1460
	ds_read_b32 v211, v67 offset:1720
	ds_read_b32 v212, v67 offset:1980
	ds_read_b32 v213, v67 offset:192
	ds_read_b32 v214, v67 offset:452
	ds_read_b32 v215, v67 offset:712
	ds_read_b32 v216, v67 offset:972
	ds_read_b32 v217, v67 offset:1232
	ds_read_b32 v218, v67 offset:1492
	ds_read_b32 v219, v67 offset:1752
	ds_read_b32 v220, v67 offset:2012
	ds_read_b32 v221, v67 offset:224
	ds_read_b32 v232, v67 offset:484
	ds_read_b32 v233, v67 offset:744
	ds_read_b32 v234, v67 offset:1004
	ds_read_b32 v235, v67 offset:1264
	ds_read_b32 v236, v67 offset:1524
	ds_read_b32 v237, v67 offset:1784
	ds_read_b32 v238, v67 offset:2044
	s_waitcnt lgkmcnt(15)
	v_cvt_pk_bf16_f32 v240, v162, v163
	v_cvt_pk_bf16_f32 v241, v164, v165
	v_cvt_pk_bf16_f32 v242, v166, v167
	v_cvt_pk_bf16_f32 v243, v168, v169
	global_store_dwordx4 v65, v[240:243], s[48:49] sc1
	s_add_u32 s48, s48, s2
	s_addc_u32 s49, s49, 0
	s_waitcnt lgkmcnt(15)
	v_cvt_pk_bf16_f32 v244, v170, v171
	v_cvt_pk_bf16_f32 v245, v172, v173
	v_cvt_pk_bf16_f32 v246, v174, v175
	v_cvt_pk_bf16_f32 v247, v176, v177
	global_store_dwordx4 v65, v[244:247], s[48:49] sc1
	s_add_u32 s48, s48, s2
	s_addc_u32 s49, s49, 0
	s_waitcnt lgkmcnt(15)
	v_cvt_pk_bf16_f32 v240, v178, v179
	v_cvt_pk_bf16_f32 v241, v180, v181
	v_cvt_pk_bf16_f32 v242, v182, v183
	v_cvt_pk_bf16_f32 v243, v184, v185
	global_store_dwordx4 v65, v[240:243], s[48:49] sc1
	s_add_u32 s48, s48, s2
	s_addc_u32 s49, s49, 0
	s_waitcnt lgkmcnt(15)
	v_cvt_pk_bf16_f32 v244, v186, v187
	v_cvt_pk_bf16_f32 v245, v191, v192
	v_cvt_pk_bf16_f32 v246, v193, v194
	v_cvt_pk_bf16_f32 v247, v195, v196
	global_store_dwordx4 v65, v[244:247], s[48:49] sc1
	s_add_u32 s48, s48, s2
	s_addc_u32 s49, s49, 0
	s_waitcnt lgkmcnt(15)
	v_cvt_pk_bf16_f32 v240, v197, v198
	v_cvt_pk_bf16_f32 v241, v199, v200
	v_cvt_pk_bf16_f32 v242, v201, v202
	v_cvt_pk_bf16_f32 v243, v203, v204
	global_store_dwordx4 v65, v[240:243], s[48:49] sc1
	s_add_u32 s48, s48, s2
	s_addc_u32 s49, s49, 0
	s_waitcnt lgkmcnt(15)
	v_cvt_pk_bf16_f32 v244, v205, v206
	v_cvt_pk_bf16_f32 v245, v207, v208
	v_cvt_pk_bf16_f32 v246, v209, v210
	v_cvt_pk_bf16_f32 v247, v211, v212
	global_store_dwordx4 v65, v[244:247], s[48:49] sc1
	s_add_u32 s48, s48, s2
	s_addc_u32 s49, s49, 0
	s_waitcnt lgkmcnt(8)
	v_cvt_pk_bf16_f32 v240, v213, v214
	v_cvt_pk_bf16_f32 v241, v215, v216
	v_cvt_pk_bf16_f32 v242, v217, v218
	v_cvt_pk_bf16_f32 v243, v219, v220
	global_store_dwordx4 v65, v[240:243], s[48:49] sc1
	s_add_u32 s48, s48, s2
	s_addc_u32 s49, s49, 0
	s_waitcnt lgkmcnt(0)
	v_cvt_pk_bf16_f32 v244, v221, v232
	v_cvt_pk_bf16_f32 v245, v233, v234
	v_cvt_pk_bf16_f32 v246, v235, v236
	v_cvt_pk_bf16_f32 v247, v237, v238
	global_store_dwordx4 v65, v[244:247], s[48:49] sc1
	s_waitcnt lgkmcnt(0)
	s_cmp_lt_u32 s11, 0x1b80
	s_cbranch_scc0 .Ltr_done_1
	s_mov_b64 s[48:49], s[20:21]
	s_mov_b32 s50, s19
	s_add_u32 s11, s11, s54
	s_cmp_lt_u32 s11, 0x1b80
	s_cbranch_scc0 .Ltr_nonext_19
	s_cmp_lt_u32 s11, 0x1080
	s_cbranch_scc0 .Ltr_B_21
	s_cmp_ge_u32 s11, 0x840
	s_cselect_b32 s2, 1, 0
	s_mul_i32 s3, s2, 0x840
	s_sub_u32 s3, s11, s3
	s_cmp_lt_u32 s3, 0x580
	s_cbranch_scc0 .Ltr_FO_22
	s_mul_i32 s4, s3, 745
	s_lshr_b32 s4, s4, 16
	s_mul_i32 s5, s4, 88
	s_sub_u32 s5, s3, s5
	s_lshr_b32 s31, s5, 2
	s_lshl_b32 s31, s31, 7
	s_bfe_u32 s32, s5, 0x10001
	s_mul_i32 s32, s32, 2816
	s_add_u32 s31, s31, s32
	s_and_b32 s32, s5, 1
	s_lshl_b32 s32, s32, 6
	s_add_u32 s31, s31, s32
	s_lshl_b32 s32, s4, 6
	s_lshl_b32 s35, s5, 6
	s_cmp_eq_u32 s2, 1
	s_cselect_b32 s36, 0x98, 0x28
	s_mov_b32 s4, 0x12000000
	s_cselect_b32 s4, 0x1f00000, s4
	s_movk_i32 s18, 0x5800
	s_movk_i32 s19, 0x800
	s_branch .Ltr_com_26

.Ltr_com_26:
	s_load_dwordx2 s[16:17], s[82:83], s36
	s_mul_i32 s5, s35, s19
	s_lshl_b32 s2, s32, 1
	s_add_u32 s5, s5, s2
	s_add_u32 s20, s74, s4
	s_addc_u32 s21, s75, 0
	s_add_u32 s20, s20, s5
	s_addc_u32 s21, s21, 0
	s_mul_i32 s5, s32, s18
	s_lshl_b32 s2, s31, 2
	s_add_u32 s5, s5, s2
	s_waitcnt lgkmcnt(0)
	s_add_u32 s16, s16, s5
	s_addc_u32 s17, s17, 0
	v_mul_lo_u32 v64, v68, s18
	v_add_u32_e32 v64, v64, v69
	s_lshl_b32 s2, s18, 2
	global_load_dwordx4 v[0:3], v64, s[16:17]
	s_add_u32 s16, s16, s2
	s_addc_u32 s17, s17, 0
	global_load_dwordx4 v[4:7], v64, s[16:17]
	s_add_u32 s16, s16, s2
	s_addc_u32 s17, s17, 0
	global_load_dwordx4 v[8:11], v64, s[16:17]
	s_add_u32 s16, s16, s2
	s_addc_u32 s17, s17, 0
	global_load_dwordx4 v[12:15], v64, s[16:17]
	s_add_u32 s16, s16, s2
	s_addc_u32 s17, s17, 0
	global_load_dwordx4 v[16:19], v64, s[16:17]
	s_add_u32 s16, s16, s2
	s_addc_u32 s17, s17, 0
	global_load_dwordx4 v[20:23], v64, s[16:17]
	s_add_u32 s16, s16, s2
	s_addc_u32 s17, s17, 0
	global_load_dwordx4 v[24:27], v64, s[16:17]
	s_add_u32 s16, s16, s2
	s_addc_u32 s17, s17, 0
	global_load_dwordx4 v[28:31], v64, s[16:17]
	s_add_u32 s16, s16, s2
	s_addc_u32 s17, s17, 0
	global_load_dwordx4 v[32:35], v64, s[16:17]
	s_add_u32 s16, s16, s2
	s_addc_u32 s17, s17, 0
	global_load_dwordx4 v[36:39], v64, s[16:17]
	s_add_u32 s16, s16, s2
	s_addc_u32 s17, s17, 0
	global_load_dwordx4 v[40:43], v64, s[16:17]
	s_add_u32 s16, s16, s2
	s_addc_u32 s17, s17, 0
	global_load_dwordx4 v[44:47], v64, s[16:17]
	s_add_u32 s16, s16, s2
	s_addc_u32 s17, s17, 0
	global_load_dwordx4 v[48:51], v64, s[16:17]
	s_add_u32 s16, s16, s2
	s_addc_u32 s17, s17, 0
	global_load_dwordx4 v[52:55], v64, s[16:17]
	s_add_u32 s16, s16, s2
	s_addc_u32 s17, s17, 0
	global_load_dwordx4 v[56:59], v64, s[16:17]
	s_add_u32 s16, s16, s2
	s_addc_u32 s17, s17, 0
	global_load_dwordx4 v[60:63], v64, s[16:17]
	s_cmp_eq_u32 s51, 1
	s_cbranch_scc1 .Ltr_f1_27
	s_waitcnt vmcnt(24)
	s_branch .Ltr_proc_20

.Ltr_proc_20:
	s_mov_b32 s51, 0
	ds_write_b32 v66, v98 offset:0
	ds_write_b32 v66, v99 offset:4
	ds_write_b32 v66, v100 offset:8
	ds_write_b32 v66, v101 offset:12
	ds_write_b32 v66, v102 offset:1040
	ds_write_b32 v66, v103 offset:1044
	ds_write_b32 v66, v104 offset:1048
	ds_write_b32 v66, v105 offset:1052
	ds_write_b32 v66, v106 offset:2080
	ds_write_b32 v66, v107 offset:2084
	ds_write_b32 v66, v108 offset:2088
	ds_write_b32 v66, v109 offset:2092
	ds_write_b32 v66, v110 offset:3120
	ds_write_b32 v66, v111 offset:3124
	ds_write_b32 v66, v112 offset:3128
	ds_write_b32 v66, v113 offset:3132
	ds_write_b32 v66, v114 offset:4160
	ds_write_b32 v66, v115 offset:4164
	ds_write_b32 v66, v116 offset:4168
	ds_write_b32 v66, v117 offset:4172
	ds_write_b32 v66, v118 offset:5200
	ds_write_b32 v66, v119 offset:5204
	ds_write_b32 v66, v120 offset:5208
	ds_write_b32 v66, v121 offset:5212
	ds_write_b32 v66, v122 offset:6240
	ds_write_b32 v66, v123 offset:6244
	ds_write_b32 v66, v124 offset:6248
	ds_write_b32 v66, v125 offset:6252
	ds_write_b32 v66, v126 offset:7280
	ds_write_b32 v66, v127 offset:7284
	ds_write_b32 v66, v128 offset:7288
	ds_write_b32 v66, v129 offset:7292
	ds_write_b32 v66, v130 offset:8320
	ds_write_b32 v66, v131 offset:8324
	ds_write_b32 v66, v132 offset:8328
	ds_write_b32 v66, v133 offset:8332
	ds_write_b32 v66, v134 offset:9360
	ds_write_b32 v66, v135 offset:9364
	ds_write_b32 v66, v136 offset:9368
	ds_write_b32 v66, v137 offset:9372
	ds_write_b32 v66, v138 offset:10400
	ds_write_b32 v66, v139 offset:10404
	ds_write_b32 v66, v140 offset:10408
	ds_write_b32 v66, v141 offset:10412
	ds_write_b32 v66, v142 offset:11440
	ds_write_b32 v66, v143 offset:11444
	ds_write_b32 v66, v144 offset:11448
	ds_write_b32 v66, v145 offset:11452
	ds_write_b32 v66, v146 offset:12480
	ds_write_b32 v66, v147 offset:12484
	ds_write_b32 v66, v148 offset:12488
	ds_write_b32 v66, v149 offset:12492
	ds_write_b32 v66, v150 offset:13520
	ds_write_b32 v66, v151 offset:13524
	ds_write_b32 v66, v152 offset:13528
	ds_write_b32 v66, v153 offset:13532
	ds_write_b32 v66, v154 offset:14560
	ds_write_b32 v66, v155 offset:14564
	ds_write_b32 v66, v156 offset:14568
	ds_write_b32 v66, v157 offset:14572
	ds_write_b32 v66, v158 offset:15600
	ds_write_b32 v66, v159 offset:15604
	ds_write_b32 v66, v160 offset:15608
	ds_write_b32 v66, v161 offset:15612
	s_waitcnt lgkmcnt(0)
	v_mul_lo_u32 v65, v70, s50
	v_add_u32_e32 v65, v65, v71
	s_lshl_b32 s2, s50, 3
	ds_read_b32 v162, v67 offset:0
	ds_read_b32 v163, v67 offset:260
	ds_read_b32 v164, v67 offset:520
	ds_read_b32 v165, v67 offset:780
	ds_read_b32 v166, v67 offset:1040
	ds_read_b32 v167, v67 offset:1300
	ds_read_b32 v168, v67 offset:1560
	ds_read_b32 v169, v67 offset:1820
	ds_read_b32 v170, v67 offset:32
	ds_read_b32 v171, v67 offset:292
	ds_read_b32 v172, v67 offset:552
	ds_read_b32 v173, v67 offset:812
	ds_read_b32 v174, v67 offset:1072
	ds_read_b32 v175, v67 offset:1332
	ds_read_b32 v176, v67 offset:1592
	ds_read_b32 v177, v67 offset:1852
	ds_read_b32 v178, v67 offset:64
	ds_read_b32 v179, v67 offset:324
	ds_read_b32 v180, v67 offset:584
	ds_read_b32 v181, v67 offset:844
	ds_read_b32 v182, v67 offset:1104
	ds_read_b32 v183, v67 offset:1364
	ds_read_b32 v184, v67 offset:1624
	ds_read_b32 v185, v67 offset:1884
	ds_read_b32 v186, v67 offset:96
	ds_read_b32 v187, v67 offset:356
	ds_read_b32 v191, v67 offset:616
	ds_read_b32 v192, v67 offset:876
	ds_read_b32 v193, v67 offset:1136
	ds_read_b32 v194, v67 offset:1396
	ds_read_b32 v195, v67 offset:1656
	ds_read_b32 v196, v67 offset:1916
	ds_read_b32 v197, v67 offset:128
	ds_read_b32 v198, v67 offset:388
	ds_read_b32 v199, v67 offset:648
	ds_read_b32 v200, v67 offset:908
	ds_read_b32 v201, v67 offset:1168
	ds_read_b32 v202, v67 offset:1428
	ds_read_b32 v203, v67 offset:1688
	ds_read_b32 v204, v67 offset:1948
	ds_read_b32 v205, v67 offset:160
	ds_read_b32 v206, v67 offset:420
	ds_read_b32 v207, v67 offset:680
	ds_read_b32 v208, v67 offset:940
	ds_read_b32 v209, v67 offset:1200
	ds_read_b32 v210, v67 offset:1460
	ds_read_b32 v211, v67 offset:1720
	ds_read_b32 v212, v67 offset:1980
	ds_read_b32 v213, v67 offset:192
	ds_read_b32 v214, v67 offset:452
	ds_read_b32 v215, v67 offset:712
	ds_read_b32 v216, v67 offset:972
	ds_read_b32 v217, v67 offset:1232
	ds_read_b32 v218, v67 offset:1492
	ds_read_b32 v219, v67 offset:1752
	ds_read_b32 v220, v67 offset:2012
	ds_read_b32 v221, v67 offset:224
	ds_read_b32 v232, v67 offset:484
	ds_read_b32 v233, v67 offset:744
	ds_read_b32 v234, v67 offset:1004
	ds_read_b32 v235, v67 offset:1264
	ds_read_b32 v236, v67 offset:1524
	ds_read_b32 v237, v67 offset:1784
	ds_read_b32 v238, v67 offset:2044
	s_waitcnt lgkmcnt(15)
	v_cvt_pk_bf16_f32 v240, v162, v163
	v_cvt_pk_bf16_f32 v241, v164, v165
	v_cvt_pk_bf16_f32 v242, v166, v167
	v_cvt_pk_bf16_f32 v243, v168, v169
	global_store_dwordx4 v65, v[240:243], s[48:49] sc1
	s_add_u32 s48, s48, s2
	s_addc_u32 s49, s49, 0
	s_waitcnt lgkmcnt(15)
	v_cvt_pk_bf16_f32 v244, v170, v171
	v_cvt_pk_bf16_f32 v245, v172, v173
	v_cvt_pk_bf16_f32 v246, v174, v175
	v_cvt_pk_bf16_f32 v247, v176, v177
	global_store_dwordx4 v65, v[244:247], s[48:49] sc1
	s_add_u32 s48, s48, s2
	s_addc_u32 s49, s49, 0
	s_waitcnt lgkmcnt(15)
	v_cvt_pk_bf16_f32 v240, v178, v179
	v_cvt_pk_bf16_f32 v241, v180, v181
	v_cvt_pk_bf16_f32 v242, v182, v183
	v_cvt_pk_bf16_f32 v243, v184, v185
	global_store_dwordx4 v65, v[240:243], s[48:49] sc1
	s_add_u32 s48, s48, s2
	s_addc_u32 s49, s49, 0
	s_waitcnt lgkmcnt(15)
	v_cvt_pk_bf16_f32 v244, v186, v187
	v_cvt_pk_bf16_f32 v245, v191, v192
	v_cvt_pk_bf16_f32 v246, v193, v194
	v_cvt_pk_bf16_f32 v247, v195, v196
	global_store_dwordx4 v65, v[244:247], s[48:49] sc1
	s_add_u32 s48, s48, s2
	s_addc_u32 s49, s49, 0
	s_waitcnt lgkmcnt(15)
	v_cvt_pk_bf16_f32 v240, v197, v198
	v_cvt_pk_bf16_f32 v241, v199, v200
	v_cvt_pk_bf16_f32 v242, v201, v202
	v_cvt_pk_bf16_f32 v243, v203, v204
	global_store_dwordx4 v65, v[240:243], s[48:49] sc1
	s_add_u32 s48, s48, s2
	s_addc_u32 s49, s49, 0
	s_waitcnt lgkmcnt(15)
	v_cvt_pk_bf16_f32 v244, v205, v206
	v_cvt_pk_bf16_f32 v245, v207, v208
	v_cvt_pk_bf16_f32 v246, v209, v210
	v_cvt_pk_bf16_f32 v247, v211, v212
	global_store_dwordx4 v65, v[244:247], s[48:49] sc1
	s_add_u32 s48, s48, s2
	s_addc_u32 s49, s49, 0
	s_waitcnt lgkmcnt(8)
	v_cvt_pk_bf16_f32 v240, v213, v214
	v_cvt_pk_bf16_f32 v241, v215, v216
	v_cvt_pk_bf16_f32 v242, v217, v218
	v_cvt_pk_bf16_f32 v243, v219, v220
	global_store_dwordx4 v65, v[240:243], s[48:49] sc1
	s_add_u32 s48, s48, s2
	s_addc_u32 s49, s49, 0
	s_waitcnt lgkmcnt(0)
	v_cvt_pk_bf16_f32 v244, v221, v232
	v_cvt_pk_bf16_f32 v245, v233, v234
	v_cvt_pk_bf16_f32 v246, v235, v236
	v_cvt_pk_bf16_f32 v247, v237, v238
	global_store_dwordx4 v65, v[244:247], s[48:49] sc1
	s_waitcnt lgkmcnt(0)
	s_cmp_lt_u32 s11, 0x1b80
	s_cbranch_scc0 .Ltr_done_1
	s_branch .Ltr_loop_8
.Ltr_done_1:
.LBB0_334:
	v_readlane_b32 s2, v250, 15
	s_nop 1
	v_add_u32_e32 v2, s2, v190
	s_mov_b32 s2, 0x8000
	v_cmp_gt_i32_e32 vcc, s2, v2
	s_and_saveexec_b64 s[12:13], vcc
	s_cbranch_execz .LBB0_353
	v_readlane_b32 s2, v254, 22
	s_mov_b64 s[18:19], 0
	s_nop 0
	v_lshl_add_u32 v3, v190, 3, s2
	s_branch .LBB0_337
